# FFN-up idle WG extras 2 (with sc1 nt loads)
# speedup vs baseline: 1.0032x; 1.0027x over previous
; __global__ void __launch_bounds__(NWAVES * 64, 2) mega_fwd(Args A) {
;     ...
;     float* X = (float*)(ws + WS_X); bf16* H = (bf16*)(ws + WS_H); bf16* ACT = (bf16*)(ws + WS_ACT); bf16* PROJ = (bf16*)(ws + WS_PROJ);
;     bf16* Y = (bf16*)(ws + WS_Y); float* MACC = (float*)(ws + WS_MACC); bf16* MB = (bf16*)(ws + WS_MB); float* GO = (float*)(ws + WS_GO);
;     const float* COS = (const float*)(ws + WS_ROPE); const float* SIN = COS + (size_t)NTOK * 32;
;     { int t_ = threadIdx.x; asm volatile("" : "+v"(t_)); const int w_ = __builtin_amdgcn_readfirstlane(t_ >> 6); p0_prologue(A, lds, bx * NWAVES + w_, G * NWAVES, w_, t_ & 63); }
;     conv_until(A, lds, TL_WO1, 0);
;     xcd_barrier(bar);
; #pragma unroll 1
;     for (int step = 0; step < 3 * DEPTH; ++step) {
;         const int l = step / 3, kind = step - 3 * l;
;         unsigned char* wl = ws + WS_W + (size_t)l * LW_END;
;         const unsigned long long* ssq = (const unsigned long long*)(ws + WS_CTL + CTL_SSQ) + (size_t)step * NTOK; unsigned long long* ssq_next = (unsigned long long*)(ws + WS_CTL + CTL_SSQ) + (size_t)(step + 1) * NTOK;
;         if (kind != 1) {
;             { pg8::Gemm g{H, (const bf16*)(wl + (kind == 0 ? LW_WI1 : LW_WI2)), NTOK, NWI, DM}; pg8::StaticOrder S; S.init(NTOK, NWI, G, bx);
;               pg8::EpiSwiglu E{ACT, DFF, ssq};
;               pg8::gemm_phase<pg8::EpiSwiglu, pg8::StaticOrder, true, true>(lds + RING_OFF, g, S, E); }
;             { const int rem1 = ((NTOK / 256) * (NWI / 256)) % G;
;               conv_until(A, lds, l * TL_LAYER + (kind == 0 ? TL_WIN : TL_LAYER), (rem1 != 0 && bx >= rem1) ? 3 : 0); }
;             xcd_barrier(bar);
;         } else {
;             const bool std256 = (G == 256);
;             unsigned char* XB8 = ws + WS_X;
; #pragma unroll 1
;             for (int part = 0; part < 3; ++part) {
;                 bool do16, do8; int i16, n16, g8, c8, i8, n8;
;                 if (std256) { do16 = part == 0 || (part == 1 && bx < 64); i16 = part ? 2 : 0; n16 = part ? 1 : 2;
;                               do8 = (part == 1 && bx >= 64) || (part == 2 && bx < 128); g8 = part == 1 ? 192 : 128; c8 = part == 1 ? bx - 64 : bx; i8 = part == 1 ? 0 : 3; n8 = part == 1 ? 2 : 3; }
;                 else { do16 = part == 0; i16 = 0; n16 = 1 << 20; do8 = part == 1; g8 = G; c8 = bx; i8 = 0; n8 = 1 << 20; }
.LBB0_284:
	v_writelane_b32 v252, s64, 42
	s_nop 1
	v_writelane_b32 v252, s65, 43
	v_writelane_b32 v252, s66, 44
	v_writelane_b32 v252, s67, 45
	v_writelane_b32 v252, s68, 46
	v_writelane_b32 v252, s69, 47
	v_writelane_b32 v252, s70, 48
	v_writelane_b32 v252, s71, 49
	v_writelane_b32 v252, s72, 50
	v_writelane_b32 v252, s73, 51
	v_writelane_b32 v252, s74, 52
	v_writelane_b32 v252, s75, 53
	v_writelane_b32 v252, s76, 54
	v_writelane_b32 v252, s77, 55
	v_writelane_b32 v252, s78, 56
	v_writelane_b32 v252, s79, 57
	s_or_b64 exec, exec, s[0:1]
	s_cmpk_lg_i32 s95, 0x100
	s_cselect_b64 s[0:1], -1, 0
	s_and_b64 s[0:1], s[0:1], exec
	s_cselect_b32 s69, s95, 0x80
	s_add_i32 s4, s97, 0xffffff80
	s_cmpk_lg_i32 s95, 0x100
	s_cselect_b64 s[0:1], -1, 0
	s_and_b64 s[2:3], s[0:1], exec
	s_cselect_b32 s20, s97, s4
	v_readlane_b32 s4, v252, 2
	v_readlane_b32 s18, v252, 16
	v_readlane_b32 s19, v252, 17
	s_add_u32 s74, s18, 0x10000
	s_addc_u32 s2, s19, 0
	v_readlane_b32 s5, v252, 3
	v_readlane_b32 s6, v252, 4
	v_readlane_b32 s7, v252, 5
	v_readlane_b32 s8, v252, 6
	v_readlane_b32 s9, v252, 7
	v_readlane_b32 s10, v252, 8
	v_readlane_b32 s11, v252, 9
	v_readlane_b32 s12, v252, 10
	v_readlane_b32 s13, v252, 11
	v_readlane_b32 s14, v252, 12
	v_readlane_b32 s15, v252, 13
	v_readlane_b32 s16, v252, 14
	v_readlane_b32 s17, v252, 15
	v_writelane_b32 v252, s2, 58
	s_add_u32 s2, s18, 0x35e00000
	s_addc_u32 s3, s19, 0
	s_add_u32 s88, s18, 0x3b600000
	s_addc_u32 s89, s19, 0
	v_writelane_b32 v252, s2, 59
	s_add_u32 s12, s18, 0x45e00000
	s_addc_u32 s13, s19, 0
	v_writelane_b32 v252, s3, 60
	v_writelane_b32 v252, s12, 61
	s_add_u32 s2, s18, 0x4c200000
	v_writelane_b32 v252, s13, 62
	s_addc_u32 s3, s19, 0
	v_writelane_b32 v252, s2, 63
	s_waitcnt vmcnt(15)
	v_mov_b32_e32 v3, 0
	v_mov_b32_e32 v216, 1
	v_writelane_b32 v253, s3, 0
	s_add_u32 s2, s18, 0x4e200000
	s_addc_u32 s3, s19, 0
	v_writelane_b32 v253, s2, 1
	v_mov_b32_e32 v217, 0x7f7f7f7f
	v_mov_b32_e32 v225, 0x43e00000
	v_writelane_b32 v253, s3, 2
	s_add_u32 s2, s18, 0x4fa00000
	s_addc_u32 s3, s19, 0
	v_writelane_b32 v253, s2, 3
	v_mov_b64_e32 v[226:227], 0x2ff
	v_mov_b32_e32 v222, 0x41b17218
	v_writelane_b32 v253, s3, 4
	s_add_u32 s2, s18, 0x4fb00000
	s_addc_u32 s3, s19, 0
	v_writelane_b32 v253, s2, 5
	v_mbcnt_hi_u32_b32 v223, -1, v76
	v_mov_b32_e32 v224, 0xf149f2ca
	v_writelane_b32 v253, s3, 6
	s_add_u32 s2, s18, 0x200000
	v_writelane_b32 v253, s2, 7
	s_addc_u32 s2, s19, 0
	s_cmpk_lt_i32 s97, 0x580
	v_writelane_b32 v253, s2, 8
	s_cselect_b64 s[2:3], -1, 0
	v_writelane_b32 v253, s2, 9
	s_ashr_i32 s21, s97, 31
	s_movk_i32 s75, 0xc0
	v_writelane_b32 v253, s3, 10
	s_lshr_b32 s2, s21, 29
	s_add_i32 s3, s97, s2
	s_ashr_i32 s2, s3, 3
	s_and_b32 s3, s3, -8
	s_sub_i32 s5, s97, s3
	s_ashr_i32 s3, s95, 31
	s_add_u32 s6, s18, 0x4200
	v_writelane_b32 v253, s3, 11
	s_addc_u32 s7, s19, 0
	v_writelane_b32 v253, s6, 12
	s_movk_i32 s76, 0x300
	s_movk_i32 s77, 0x5400
	v_writelane_b32 v253, s7, 13
	s_add_u32 s6, s18, 0x4400
	s_addc_u32 s7, s19, 0
	v_writelane_b32 v253, s6, 14
	s_movk_i32 s81, 0x7fff
	s_mov_b32 s82, 0xffff0000
	v_writelane_b32 v253, s7, 15
	s_add_u32 s6, s18, 0x4500
	s_addc_u32 s7, s19, 0
	v_writelane_b32 v253, s6, 16
	s_movk_i32 s61, 0x1110
	s_movk_i32 s84, 0x15ff
	v_writelane_b32 v253, s7, 17
	s_add_u32 s6, s18, 0x4600
	s_addc_u32 s7, s19, 0
	v_writelane_b32 v253, s6, 18
	s_mov_b32 s85, 0xc3e00000
	s_movk_i32 s33, 0xff
	v_writelane_b32 v253, s7, 19
	s_add_u32 s6, s18, 0x4700
	s_addc_u32 s7, s19, 0
	v_writelane_b32 v253, s6, 20
	s_movk_i32 s66, 0x90
	s_mov_b32 s96, 0x2aaaaaab
	v_writelane_b32 v253, s7, 21
	s_add_u32 s6, s18, 0x4800
	s_addc_u32 s7, s19, 0
	v_writelane_b32 v253, s6, 22
	s_movk_i32 s36, 0x190
	s_movk_i32 s37, 0xff40
	v_writelane_b32 v253, s7, 23
	s_add_u32 s6, s18, 0x4900
	s_addc_u32 s7, s19, 0
	v_writelane_b32 v253, s6, 24
	s_movk_i32 s38, 0x567
	s_movk_i32 s39, 0x1500
	v_writelane_b32 v253, s7, 25
	s_add_u32 s6, s18, 0x4a00
	s_addc_u32 s7, s19, 0
	v_writelane_b32 v253, s6, 26
	s_movk_i32 s56, 0x1800
	s_movk_i32 s57, 0xc80
	v_writelane_b32 v253, s7, 27
	s_add_u32 s6, s18, 0x4b00
	s_addc_u32 s7, s19, 0
	v_writelane_b32 v253, s6, 28
	s_movk_i32 s58, 0x3ff
	s_mov_b32 s80, 0xefa18f08
	v_writelane_b32 v253, s7, 29
	s_add_u32 s6, s18, 0x4c00
	s_addc_u32 s7, s19, 0
	v_writelane_b32 v253, s6, 30
	s_mov_b32 s62, 0
	s_mov_b32 s94, 0x3e000000
	v_writelane_b32 v253, s7, 31
	s_add_u32 s6, s18, 0x4d00
	s_addc_u32 s7, s19, 0
	v_writelane_b32 v253, s6, 32
	s_waitcnt lgkmcnt(0)
	s_barrier
; __global__ void __launch_bounds__(NWAVES * 64, 2) mega_fwd(Args A) {
;     ...
;                 if (std256) { do16 = part == 0 || (part == 1 && bx < 64); i16 = part ? 2 : 0; n16 = part ? 1 : 2;
;                               do8 = (part == 1 && bx >= 64) || (part == 2 && bx < 128); g8 = part == 1 ? 192 : 128; c8 = part == 1 ? bx - 64 : bx; i8 = part == 1 ? 0 : 3; n8 = part == 1 ? 2 : 3; }
;                 else { do16 = part == 0; i16 = 0; n16 = 1 << 20; do8 = part == 1; g8 = G; c8 = bx; i8 = 0; n8 = 1 << 20; }
;                 if (do16) { pg8::Gemm g{H, (const bf16*)(wl + LW_WIN), NTOK, C_GATE, DM}; pg8::RangeOrder S; S.init(NTOK, C_GATE, G, bx); S.i0 = i16; S.n = n16;
;                     pg8::EpiProj E{PROJ, NPROJ, (const float*)A.in[7] + (size_t)l * 6144, 1 << 20, ssq, 1.0f};
;                     pg8::gemm_phase<pg8::EpiProj, pg8::RangeOrder, true, true>(lds + RING_OFF, g, S, E); }
;                 if (do8) { pg8::Gemm g{(const bf16*)XB8, (const bf16*)(wl + LW_WIN + WIN8_OFF), NTOK, 6144, DM / 2}; pg8::RangeOrder S; S.init(NTOK, 6144, g8, c8); S.i0 = i8; S.n = n8;
;                     pg8::EpiGate8 E{(unsigned char*)(PROJ + C_GATE), NPROJ * 2, (const float*)A.in[7] + (size_t)l * 6144, ssq, 1.0f / 2048.0f};
;                     pg8::gemm_phase<pg8::EpiGate8, pg8::RangeOrder, true, true, true>(lds + RING_OFF, g, S, E); }
;                 if (part == 1) xcd_barrier(bar);
;                 if (part == 2 && (!std256 || bx >= 128)) { const int mb = std256 ? bx - 128 : bx, ms = std256 ? 128 : G;
;                     if ((ms & 3) == 0) pool_units(lds, PROJ, (const bf16*)(ws + WS_WPT) + (size_t)l * 4 * 192 * 192, Y + (size_t)NTOK * BRW, mb, ms, 512);
;                     else for (int u = mb; u < 512; u += ms) pool_units(lds, PROJ, (const bf16*)(ws + WS_WPT) + (size_t)l * 4 * 192 * 192, Y + (size_t)NTOK * BRW, u, 512, 512);
;                     gla_pre_items(lds, PROJ, (const float*)A.in[11] + (size_t)l * 16 * 384, (const float*)A.in[12] + l * 384, ws + WS_GPRE, mb, ms, 512); }
;             }
;             xcd_barrier(bar);
;             if (G > 96) { if (bx < 48) gla_scan_unit(lds, ws + WS_GPRE, GO, bx);
;                           else for (int u = bx - 48; u < 256; u += G - 48) att_unit(lds, PROJ, COS, SIN, (const float*)A.in[8] + l * 12, Y, u); }
;             else { for (int u = bx; u < 48; u += G) gla_scan_unit(lds, ws + WS_GPRE, GO, u);
	v_writelane_b32 v253, s7, 33
	s_add_u32 s6, s18, 0x4e00
	s_addc_u32 s7, s19, 0
	v_writelane_b32 v253, s6, 34
	s_nop 1
	v_writelane_b32 v253, s7, 35
	s_add_u32 s6, s18, 0x4f00
	s_addc_u32 s7, s19, 0
	v_writelane_b32 v253, s6, 36
	s_nop 1
	v_writelane_b32 v253, s7, 37
	s_add_u32 s6, s18, 0x5000
	s_addc_u32 s7, s19, 0
	v_writelane_b32 v253, s6, 38
	s_nop 1
	v_writelane_b32 v253, s7, 39
	s_add_u32 s6, s18, 0x5100
	s_addc_u32 s7, s19, 0
	v_writelane_b32 v253, s6, 40
	s_nop 1
	v_writelane_b32 v253, s7, 41
	s_add_u32 s6, s18, 0x5200
	s_addc_u32 s7, s19, 0
	v_writelane_b32 v253, s6, 42
	s_nop 1
	v_writelane_b32 v253, s7, 43
	s_add_u32 s6, s18, 0x5300
	s_addc_u32 s7, s19, 0
	v_writelane_b32 v253, s6, 44
	s_nop 1
	v_writelane_b32 v253, s7, 45
	s_add_u32 s6, s18, 0x7400
	s_addc_u32 s7, s19, 0
	v_writelane_b32 v253, s6, 46
	s_nop 1
	v_writelane_b32 v253, s7, 47
	s_add_u32 s6, s18, 0x7500
	s_addc_u32 s7, s19, 0
	v_writelane_b32 v253, s6, 48
	s_cmpk_eq_i32 s95, 0x100
	s_nop 0
	v_writelane_b32 v253, s7, 49
	s_cselect_b64 s[6:7], -1, 0
	s_add_u32 s72, s18, 0x2fe00000
	s_addc_u32 s73, s19, 0
	v_writelane_b32 v253, s6, 50
	s_cmp_lt_i32 s97, 64
	s_nop 0
	v_writelane_b32 v253, s7, 51
	s_cselect_b64 s[6:7], -1, 0
	v_writelane_b32 v253, s6, 52
	s_cmp_gt_i32 s97, 63
	s_nop 0
	v_writelane_b32 v253, s7, 53
	s_cselect_b64 s[6:7], -1, 0
	v_writelane_b32 v253, s6, 54
	s_cmpk_lt_i32 s97, 0x80
	s_nop 0
	v_writelane_b32 v253, s7, 55
	s_cselect_b64 s[6:7], -1, 0
	v_writelane_b32 v253, s6, 56
	s_sub_i32 s3, s97, 64
	s_nop 0
	v_writelane_b32 v253, s7, 57
	s_add_u32 s6, s18, 0x3b602400
	v_writelane_b32 v253, s3, 58
	s_addc_u32 s7, s19, 0
	v_writelane_b32 v253, s6, 59
	s_cmpk_gt_i32 s97, 0x7f
	s_nop 0
	v_writelane_b32 v253, s7, 60
	s_cselect_b64 s[6:7], -1, 0
	s_or_b64 s[0:1], s[6:7], s[0:1]
	v_writelane_b32 v253, s0, 61
	s_nop 1
	v_writelane_b32 v253, s1, 62
	s_and_b32 s0, s69, 3
	s_cmp_lg_u32 s0, 0
	s_cselect_b64 s[0:1], -1, 0
	v_writelane_b32 v253, s0, 63
	s_cmpk_lt_i32 s20, 0x200
	s_nop 0
	v_writelane_b32 v254, s1, 0
	s_cselect_b64 s[0:1], -1, 0
	v_writelane_b32 v254, s0, 1
	s_nop 1
	v_writelane_b32 v254, s1, 2
	s_add_u32 s0, s18, 0x46a00000
	s_addc_u32 s1, s19, 0
	v_writelane_b32 v254, s0, 3
	s_and_b32 s4, s20, 3
	s_nop 0
	v_writelane_b32 v254, s1, 4
	s_mul_i32 s0, s4, 0x12000
	s_add_u32 s0, s34, s0
	v_writelane_b32 v254, s0, 5
	v_writelane_b32 v254, s34, 6
	s_addc_u32 s0, s35, 0
	s_lshl_b32 s68, 2, s4
	v_writelane_b32 v254, s35, 7
	v_writelane_b32 v254, s0, 8
	s_lshl_b32 s1, s20, 4
	s_lshl_b32 s0, s69, 4
	s_add_u32 s22, s18, 0x4fc00000
	v_writelane_b32 v254, s0, 9
	s_addc_u32 s23, s19, 0
	s_lshl_b32 s0, s20, 6
	s_and_b32 s0, s0, 0x7c0
	v_writelane_b32 v254, s1, 10
	s_and_b32 s1, s1, 0xfffff800
	s_or_b32 s0, s1, s0
	s_ashr_i32 s1, s0, 31
	v_writelane_b32 v254, s0, 11
	s_bfe_u32 s3, s20, 0x20005
	s_mov_b32 s35, 0
	v_writelane_b32 v254, s1, 12
	s_mul_i32 s0, s3, 0x60
	v_writelane_b32 v254, s20, 13
	s_add_i32 s1, s0, 0x920
	v_writelane_b32 v254, s1, 14
	v_writelane_b32 v254, s0, 15
	s_bitset1_b32 s0, 11
	s_cmpk_lt_i32 s95, 0x61
	v_writelane_b32 v254, s0, 16
	s_cselect_b64 s[0:1], -1, 0
	s_cmpk_gt_i32 s95, 0x60
	v_writelane_b32 v254, s0, 17
	s_cselect_b64 s[6:7], -1, 0
	s_cmp_lt_i32 s97, 48
	v_writelane_b32 v254, s1, 18
	s_cselect_b64 s[0:1], -1, 0
	v_writelane_b32 v254, s0, 19
	s_cmpk_lt_i32 s97, 0x100
	s_nop 0
	v_writelane_b32 v254, s1, 20
	s_cselect_b64 s[0:1], -1, 0
	v_writelane_b32 v254, s0, 21
	s_nop 1
	v_writelane_b32 v254, s1, 22
	s_sub_i32 s0, s97, 48
	v_writelane_b32 v254, s0, 23
	s_cmpk_lt_i32 s97, 0x130
	s_mul_hi_i32 s0, s97, 0x55555556
	s_cselect_b64 s[8:9], -1, 0
	s_lshr_b32 s1, s0, 31
	s_add_i32 s10, s0, s1
	s_mul_i32 s0, s10, -3
	s_add_i32 s0, s0, s97
	v_writelane_b32 v254, s8, 24
	s_lshl_b32 s1, s0, 13
	s_add_i32 s1, s1, 0x8000
	v_writelane_b32 v254, s9, 25
	v_writelane_b32 v254, s1, 26
	s_sub_i32 s1, s95, 48
	v_writelane_b32 v254, s1, 27
	s_lshl_b32 s8, s10, 5
	s_mul_i32 s1, s10, 0x1c4000
	v_writelane_b32 v254, s8, 28
	s_mul_hi_i32 s8, s8, 0xe200
	s_add_u32 s14, s22, s1
	s_addc_u32 s15, s23, s8
	s_add_u32 s8, s14, 0xe000
	v_writelane_b32 v254, s14, 29
	s_addc_u32 s9, s15, 0
	s_lshl_b32 s1, s10, 9
	s_lshl_b32 s0, s0, 6
	v_writelane_b32 v254, s15, 30
	s_and_b32 s11, s1, 0xfffff800
	s_ashr_i32 s1, s0, 31
	v_writelane_b32 v254, s8, 31
	s_cmp_gt_i32 s97, 47
	s_nop 0
	v_writelane_b32 v254, s9, 32
	s_cselect_b64 s[8:9], -1, 0
	v_writelane_b32 v254, s8, 33
	s_mov_b64 s[14:15], s[6:7]
	s_add_i32 s6, s97, s95
	s_addk_i32 s6, 0xffa0
	v_writelane_b32 v254, s9, 34
	s_cmpk_lt_i32 s6, 0x100
	s_cselect_b32 s8, 2, 4
	v_writelane_b32 v254, s14, 35
	s_and_b64 s[6:7], s[14:15], exec
	s_cselect_b32 s6, s8, 0
	v_writelane_b32 v254, s15, 36
	v_writelane_b32 v254, s6, 37
	s_add_u32 s6, s18, 0x47600000
	v_writelane_b32 v254, s6, 38
	s_addc_u32 s6, s19, 0
	v_writelane_b32 v254, s6, 39
	s_lshl_b32 s14, s95, 5
	s_lshl_b32 s6, s5, 5
	s_cmp_lt_i32 s5, 0
	s_movk_i32 s7, 0xb1
;     __host__ __device__ bool next(int i, Unit& u) const {
;         const long L = (long)i * G + c; if (L >= nwg) return false;
;         int wgid = (int)L; { const int q = nwg / NXCD, r = nwg % NXCD, xcd = wgid % NXCD, off = wgid / NXCD; wgid = (xcd < r ? xcd * (q + 1) : r * (q + 1) + (xcd - r) * q) + off; }
;         const int nig = WGM * nN, gid = wgid / nig, fm = gid * WGM, gsz = (nM - fm) < WGM ? (nM - fm) : WGM;
;         u.pm = fm + ((wgid % nig) % gsz); u.pn = (wgid % nig) / gsz; u.seg = 0; return true;
; __global__ void __launch_bounds__(NWAVES * 64, 2) mega_fwd(Args A) {
;     ...
;             { const int rem1 = ((NTOK / 256) * (NWI / 256)) % G;
;               conv_until(A, lds, l * TL_LAYER + (kind == 0 ? TL_WIN : TL_LAYER), (rem1 != 0 && bx >= rem1) ? 3 : 0); }
	s_cselect_b32 s7, s7, 0xb0
	s_mul_i32 s7, s5, s7
	s_mul_i32 s5, s5, 33
	s_cselect_b32 s5, s5, s6
	s_add_i32 s7, s7, s2
	s_mul_hi_i32 s6, s7, 0x2e8ba2e9
	s_lshr_b32 s8, s6, 31
	s_ashr_i32 s6, s6, 6
	s_add_i32 s6, s6, s8
	s_mul_i32 s8, s6, 0x160
	s_sub_i32 s7, s7, s8
	s_bfe_u32 s8, s7, 0x3001c
	s_add_i32 s8, s7, s8
	s_and_b32 s9, s8, 0xfff8
	s_sub_i32 s7, s7, s9
	s_lshl_b32 s6, s6, 3
	s_sext_i32_i16 s8, s8
	s_sext_i32_i16 s7, s7
	s_add_i32 s16, s6, s7
	s_ashr_i32 s6, s8, 3
	v_writelane_b32 v254, s6, 40
	s_lshr_b32 s6, s8, 3
	s_bfe_i64 s[6:7], s[6:7], 0x100000
	s_lshl_b64 s[6:7], s[6:7], 20
	v_writelane_b32 v254, s6, 41
	s_ashr_i32 s17, s16, 31
	s_nop 0
	v_writelane_b32 v254, s7, 42
	s_mov_b32 s6, s16
	v_writelane_b32 v254, s6, 43
	s_nop 1
	v_writelane_b32 v254, s7, 44
	s_lshl_b64 s[6:7], s[16:17], 20
	s_add_u32 s6, s90, s6
	s_addc_u32 s7, s91, s7
	s_add_u32 s8, s6, 0x80000
	s_addc_u32 s9, s7, 0
	v_writelane_b32 v254, s8, 45
	s_nop 1
	v_writelane_b32 v254, s9, 46
	s_add_u32 s8, s6, 0x2000
	v_writelane_b32 v254, s6, 47
	s_addc_u32 s9, s7, 0
	s_add_i32 s2, s5, s2
	s_ashr_i32 s5, s2, 31
	s_lshr_b32 s5, s5, 26
	s_add_i32 s5, s2, s5
	v_writelane_b32 v254, s7, 48
	s_and_b32 s6, s5, 0xffc0
	s_sub_i32 s2, s2, s6
	s_bfe_i32 s6, s2, 0x80000
	s_bfe_u32 s6, s6, 0x3000c
	s_add_i32 s6, s2, s6
	s_and_b32 s7, s6, 0xf8
	s_sub_i32 s2, s2, s7
	s_ashr_i32 s5, s5, 6
	s_lshl_b32 s5, s5, 3
	s_sext_i32_i8 s2, s2
	s_add_i32 s5, s5, s2
	s_bfe_i32 s2, s6, 0x80000
	v_writelane_b32 v254, s8, 49
	s_sext_i32_i16 s2, s2
	s_ashr_i32 s6, s2, 3
	v_writelane_b32 v254, s9, 50
	s_lshr_b32 s2, s2, 3
	v_writelane_b32 v254, s6, 51
	s_bfe_i64 s[6:7], s[2:3], 0x100000
	v_writelane_b32 v254, s6, 52
	s_mul_hi_i32 s2, s5, 0x60000
	s_nop 0
	v_writelane_b32 v254, s7, 53
	v_writelane_b32 v254, s5, 54
	s_mul_i32 s5, s5, 0x60000
	s_add_u32 s6, s12, s5
	s_addc_u32 s7, s13, s2
	s_add_u32 s8, s6, 0x30000
	s_addc_u32 s9, s7, 0
	v_writelane_b32 v254, s8, 55
	s_nop 1
	v_writelane_b32 v254, s9, 56
	s_add_u32 s8, s6, 0x2000
	v_writelane_b32 v254, s6, 57
	s_addc_u32 s9, s7, 0
	s_abs_i32 s2, s95
	v_cvt_f32_u32_e32 v1, s2
	v_writelane_b32 v254, s7, 58
	s_sub_i32 s5, 0, s2
	v_writelane_b32 v254, s8, 59
	v_rcp_iflag_f32_e32 v1, v1
	s_nop 0
	v_writelane_b32 v254, s9, 60
	v_mul_f32_e32 v1, 0x4f7ffffe, v1
	v_cvt_u32_f32_e32 v1, v1
	s_nop 0
	v_readfirstlane_b32 s6, v1
	s_mul_i32 s5, s5, s6
	s_mul_hi_u32 s5, s6, s5
	s_add_i32 s6, s6, s5
	s_mul_hi_u32 s5, s6, 0x580
	s_mul_i32 s5, s5, s2
	s_sub_i32 s5, 0x580, s5
	s_sub_i32 s6, s5, s2
	s_cmp_ge_u32 s5, s2
	s_cselect_b32 s5, s6, s5
	s_sub_i32 s6, s5, s2
	s_cmp_ge_u32 s5, s2
	s_cselect_b32 s2, s6, s5
	s_cmp_lg_u32 s2, 0
	s_cselect_b64 s[6:7], -1, 0
	s_cmp_ge_i32 s97, s2
	s_cselect_b64 s[8:9], -1, 0
	s_and_b64 s[6:7], s[6:7], s[8:9]
	s_mul_i32 s2, s4, 0xc0
	v_writelane_b32 v254, s6, 61
	s_and_b64 s[4:5], s[6:7], exec
	s_cselect_b32 s4, 2, 0
	v_writelane_b32 v254, s7, 62
	v_writelane_b32 v255, s2, 0
	s_lshl_b32 s2, s2, 1
	v_writelane_b32 v254, s4, 63
	s_add_u32 s4, s88, s2
	s_addc_u32 s5, s89, 0
	v_writelane_b32 v255, s4, 1
	s_and_b32 s2, s10, 3
	s_mulk_i32 s2, 0x300
	v_writelane_b32 v255, s5, 2
	s_mul_i32 s4, s11, 0xc00
	s_lshl_b32 s5, s97, 6
	s_or_b32 s2, s4, s2
	s_lshl_b64 s[0:1], s[0:1], 2
	v_writelane_b32 v255, s5, 3
	s_lshl_b32 s5, s95, 6
	s_mul_hi_i32 s4, s11, 0xc00
	s_add_u32 s0, s2, s0
	s_addc_u32 s1, s4, s1
	s_add_u32 s0, s18, s0
	v_writelane_b32 v255, s5, 4
	s_addc_u32 s1, s19, s1
	v_writelane_b32 v255, s0, 5
	s_mul_i32 s2, s95, 0x18000
	s_add_i32 s93, 0, 0x20180
	v_writelane_b32 v255, s1, 6
	s_mul_i32 s0, s3, 0xc0
	s_mul_hi_i32 s3, s14, 0xc00
	v_writelane_b32 v255, s2, 7
	s_lshl_b32 s1, s97, 9
	s_lshl_b32 s0, s0, 1
	v_writelane_b32 v255, s3, 8
	s_mul_i32 s2, s95, 0xa8000
	v_writelane_b32 v255, s14, 9
	s_mul_hi_i32 s3, s14, 0x5400
	v_writelane_b32 v255, s2, 10
	s_add_i32 s60, 0, 0x20184
	v_mov_b32_e32 v1, 0x358637bd
	v_writelane_b32 v255, s3, 11
	v_writelane_b32 v255, s1, 12
	s_lshl_b32 s1, s95, 11
	v_writelane_b32 v255, s1, 13
	s_lshl_b32 s1, s95, 4
	v_writelane_b32 v255, s1, 14
	s_lshl_b32 s1, s95, 10
	v_writelane_b32 v255, s1, 15
	s_lshl_b32 s1, s95, 9
	v_writelane_b32 v255, s1, 16
	s_add_i32 s1, 0, 0x20160
	v_writelane_b32 v255, s1, 17
	s_add_i32 s1, 0, 0x20164
	v_writelane_b32 v255, s1, 18
	s_add_i32 s1, 0, 0x2d00
	v_writelane_b32 v255, s1, 19
	v_writelane_b32 v255, s0, 20
	s_add_i32 s64, 0, 0x12600
	s_nop 0
	v_writelane_b32 v255, s1, 21
	s_add_i32 s0, 0, 0xf000
	v_writelane_b32 v255, s0, 22
	s_add_i32 s0, 0, 0x8800
	v_writelane_b32 v255, s0, 23
	v_writelane_b32 v255, s90, 24
	s_nop 1
	v_writelane_b32 v255, s91, 25
	v_writelane_b32 v255, s69, 26
	v_writelane_b32 v255, s88, 27
	s_nop 1
	v_writelane_b32 v255, s89, 28
	v_writelane_b32 v255, s21, 29
	v_writelane_b32 v255, s22, 30
	v_writelane_b32 v255, s23, 31
	v_writelane_b32 v255, s93, 32
	v_writelane_b32 v255, s60, 33
	v_writelane_b32 v255, s92, 34
	s_nop 1
	v_writelane_b32 v255, s93, 35
	s_branch .LBB0_287
